# k4_glaprep
# speedup vs baseline: 1.0535x; 1.0095x over previous
; DI float bf2f(u16 u) { return __uint_as_float(((unsigned)u) << 16); }
; DI void phase_gla_prep(const Params& p, char* smem) {
;     ...
;       const int col = cp * 256 + tid;
;       float w[16];
; #pragma unroll
;       for (int j = 0; j < 16; ++j) w[j] = wg[j * 512 + col];
;       const float bgc = bg[col];
;       float c = 0.f;
;       for (int tt = 0; tt < nrow; ++tt) {
;         float z = bgc;
; #pragma unroll
;         for (int j = 0; j < 16; ++j) z += g1s[tt * 16 + j] * w[j];
;         const float la = (fminf(z, 0.f) - log1pf(__expf(-fabsf(z)))) * (1.f / 16.f);
;         c += la;
;         const float E = __expf(c);
;         u16* rp = proj1 + (size_t)(b * LT + t0 + tt) * 3088;
;         const float q = bf2f(rp[col]), k = bf2f(rp[512 + col]);
.LBB0_561:
	v_add_u32_e32 v0, s29, v183
	v_lshlrev_b64 v[16:17], 2, v[0:1]
	v_lshl_add_u64 v[8:9], s[46:47], 0, v[16:17]
	v_add_co_u32_e32 v6, vcc, 0x1000, v8
	v_lshl_add_u64 v[16:17], s[48:49], 0, v[16:17]
	s_nop 0
	v_addc_co_u32_e32 v7, vcc, 0, v9, vcc
	v_add_co_u32_e32 v10, vcc, 0x2000, v8
	s_xor_b64 s[18:19], s[12:13], -1
	s_nop 0
	v_addc_co_u32_e32 v11, vcc, 0, v9, vcc
	v_add_co_u32_e32 v12, vcc, 0x3000, v8
	s_mov_b32 s29, 0
	s_nop 0
	v_addc_co_u32_e32 v13, vcc, 0, v9, vcc
	global_load_dword v25, v[8:9], off
	global_load_dword v26, v[8:9], off offset:2048
	global_load_dword v27, v[6:7], off
	global_load_dword v28, v[6:7], off offset:2048
	global_load_dword v29, v[10:11], off
	global_load_dword v30, v[10:11], off offset:2048
	s_nop 0
	global_load_dword v6, v[12:13], off
	global_load_dword v7, v[12:13], off offset:2048
	v_add_co_u32_e32 v10, vcc, 0x4000, v8
	s_mov_b32 s30, s15
	s_nop 0
	v_addc_co_u32_e32 v11, vcc, 0, v9, vcc
	v_add_co_u32_e32 v12, vcc, 0x5000, v8
	s_nop 1
	v_addc_co_u32_e32 v13, vcc, 0, v9, vcc
	v_add_co_u32_e32 v14, vcc, 0x6000, v8
	s_nop 1
	v_addc_co_u32_e32 v15, vcc, 0, v9, vcc
	v_add_co_u32_e32 v32, vcc, 0x7000, v8
	s_nop 1
	v_addc_co_u32_e32 v33, vcc, 0, v9, vcc
	global_load_dword v8, v[10:11], off
	global_load_dword v9, v[10:11], off offset:2048
	s_nop 0
	global_load_dword v10, v[12:13], off
	global_load_dword v11, v[12:13], off offset:2048
	s_nop 0
	global_load_dword v12, v[14:15], off
	global_load_dword v13, v[14:15], off offset:2048
	s_nop 0
	global_load_dword v14, v[32:33], off
	global_load_dword v15, v[32:33], off offset:2048
	global_load_dword v31, v[16:17], off
	v_lshl_add_u64 v[16:17], v[0:1], 1, s[52:53]
	v_mov_b32_e32 v32, 0
	v_mov_b32_e32 v33, v3
	v_mad_i64_i32 v[254:255], vcc, s30, v24, v[16:17]
	global_load_ushort v52, v[254:255], off
	global_load_ushort v53, v[254:255], off offset:1024
	s_waitcnt vmcnt(0)
; DI float bf2f(u16 u) { return __uint_as_float(((unsigned)u) << 16); }
; DI void phase_gla_prep(const Params& p, char* smem) {
;     ...
;       for (int tt = 0; tt < nrow; ++tt) {
;         float z = bgc;
; #pragma unroll
;         for (int j = 0; j < 16; ++j) z += g1s[tt * 16 + j] * w[j];
;         const float la = (fminf(z, 0.f) - log1pf(__expf(-fabsf(z)))) * (1.f / 16.f);
;         c += la;
;         const float E = __expf(c);
;         u16* rp = proj1 + (size_t)(b * LT + t0 + tt) * 3088;
;         const float q = bf2f(rp[col]), k = bf2f(rp[512 + col]);
;         rp[col] = f2bf(q * 0.08838834764831845f * E);
;         rp[512 + col] = f2bf(k / E);
;       }
.LBB0_562:
	v_mov_b32_e32 v5, s29
	ds_read_b128 v[34:37], v5
	ds_read_b128 v[38:41], v5 offset:16
	ds_read_b128 v[42:45], v5 offset:32
	ds_read_b128 v[46:49], v5 offset:48
	v_mad_i64_i32 v[50:51], s[12:13], s30, v24, v[16:17]
	s_waitcnt lgkmcnt(3)
	v_fma_f32 v5, v25, v34, v31
	v_fmac_f32_e32 v5, v26, v35
	v_fmac_f32_e32 v5, v27, v36
	v_fmac_f32_e32 v5, v28, v37
	s_waitcnt lgkmcnt(2)
	v_fmac_f32_e32 v5, v29, v38
	v_pk_mul_f32 v[40:41], v[6:7], v[40:41]
	v_fmac_f32_e32 v5, v30, v39
	v_add_f32_e32 v5, v5, v40
	s_waitcnt lgkmcnt(1)
	v_pk_mul_f32 v[42:43], v[8:9], v[42:43]
	v_add_f32_e32 v5, v5, v41
	v_add_f32_e32 v5, v5, v42
	v_pk_mul_f32 v[44:45], v[10:11], v[44:45]
	v_add_f32_e32 v5, v5, v43
	v_add_f32_e32 v5, v5, v44
	s_waitcnt lgkmcnt(0)
	v_pk_mul_f32 v[46:47], v[12:13], v[46:47]
	v_add_f32_e32 v5, v5, v45
	v_add_f32_e32 v5, v5, v46
	v_pk_mul_f32 v[48:49], v[14:15], v[48:49]
	v_add_f32_e32 v5, v5, v47
	v_add_f32_e32 v5, v5, v48
	v_add_f32_e32 v5, v5, v49
	v_min_f32_e32 v48, 0, v5
	v_mul_f32_e64 v5, |v5|, s24
	v_exp_f32_e32 v49, v5
	v_add_u32_e32 v33, -1, v33
	v_cmp_ne_u32_e64 s[12:13], 0, v33
	s_add_i32 s30, s30, 1
	v_add_f32_e32 v5, 1.0, v49
	v_add_f32_e32 v36, -1.0, v5
	v_frexp_mant_f32_e32 v37, v5
	v_cvt_f64_f32_e32 v[34:35], v5
	v_sub_f32_e32 v38, v36, v5
	v_frexp_exp_i32_f64_e32 v34, v[34:35]
	v_cmp_gt_f32_e32 vcc, s25, v37
	v_sub_f32_e32 v36, v49, v36
	v_add_f32_e32 v35, 1.0, v38
	v_subbrev_co_u32_e32 v34, vcc, 0, v34, vcc
	v_add_f32_e32 v35, v36, v35
	v_sub_u32_e32 v36, 0, v34
	v_ldexp_f32 v5, v5, v36
	v_ldexp_f32 v35, v35, v36
	v_add_f32_e32 v36, -1.0, v5
	v_add_f32_e32 v38, 1.0, v5
	v_add_f32_e32 v37, 1.0, v36
	v_add_f32_e32 v39, -1.0, v38
	v_sub_f32_e32 v37, v5, v37
	v_sub_f32_e32 v5, v5, v39
	v_add_f32_e32 v5, v35, v5
	v_add_f32_e32 v39, v35, v37
	v_add_f32_e32 v35, v38, v5
	v_rcp_f32_e32 v42, v35
	v_add_f32_e32 v37, v36, v39
	v_sub_f32_e32 v38, v35, v38
	v_sub_f32_e32 v5, v5, v38
	v_mul_f32_e32 v44, v37, v42
	v_mul_f32_e32 v38, v35, v44
	v_fma_f32 v40, v44, v35, -v38
	v_sub_f32_e32 v36, v37, v36
	v_fmac_f32_e32 v40, v44, v5
	v_sub_f32_e32 v43, v39, v36
	v_add_f32_e32 v36, v38, v40
	v_sub_f32_e32 v39, v37, v36
	v_mov_b32_e32 v41, v36
	v_pk_add_f32 v[36:37], v[36:37], v[38:39] neg_lo:[0,1] neg_hi:[0,1]
	v_cvt_f32_i32_e32 v34, v34
	v_pk_add_f32 v[36:37], v[36:37], v[40:41] neg_lo:[0,1] neg_hi:[0,1]
	v_cmp_neq_f32_e32 vcc, s27, v49
	v_add_f32_e32 v37, v43, v37
	v_add_f32_e32 v36, v36, v37
	v_add_f32_e32 v37, v39, v36
	v_mul_f32_e32 v41, v42, v37
	v_mul_f32_e32 v38, v35, v41
	v_fma_f32 v40, v41, v35, -v38
	v_sub_f32_e32 v39, v39, v37
	v_fmac_f32_e32 v40, v41, v5
	v_add_f32_e32 v43, v36, v39
	v_add_f32_e32 v45, v44, v41
	v_add_f32_e32 v36, v38, v40
	v_sub_f32_e32 v35, v45, v44
	v_sub_f32_e32 v39, v37, v36
	v_sub_f32_e32 v5, v41, v35
	v_mov_b32_e32 v41, v36
	v_pk_add_f32 v[36:37], v[36:37], v[38:39] neg_lo:[0,1] neg_hi:[0,1]
	s_add_i32 s29, s29, 64
	v_pk_add_f32 v[36:37], v[36:37], v[40:41] neg_lo:[0,1] neg_hi:[0,1]
	s_nop 0
	v_add_f32_e32 v35, v43, v37
	v_add_f32_e32 v35, v36, v35
	v_add_f32_e32 v35, v39, v35
	v_mul_f32_e32 v35, v42, v35
	v_add_f32_e32 v5, v5, v35
	v_add_f32_e32 v35, v45, v5
	v_mul_f32_e32 v36, v35, v35
	v_sub_f32_e32 v38, v35, v45
	v_fmamk_f32 v39, v36, 0x3e9b6dac, v20
	v_ldexp_f32 v37, v35, 1
	v_sub_f32_e32 v38, v5, v38
	v_mul_f32_e32 v35, v35, v36
	v_fmaak_f32 v5, v36, v39, 0x3f2aaada
	v_ldexp_f32 v41, v38, 1
	v_pk_mul_f32 v[38:39], v[34:35], v[4:5]
	s_nop 0
	v_fma_f32 v36, v34, s26, -v38
	v_fmac_f32_e32 v36, 0xb102e308, v34
	v_pk_add_f32 v[34:35], v[38:39], v[36:37]
	v_mov_b32_e32 v40, v38
	v_sub_f32_e32 v5, v35, v37
	v_sub_f32_e32 v5, v39, v5
	v_add_f32_e32 v41, v41, v5
	v_pk_add_f32 v[42:43], v[34:35], v[38:39] neg_lo:[0,1] neg_hi:[0,1]
	v_pk_add_f32 v[38:39], v[34:35], v[40:41]
	v_mov_b32_e32 v37, v34
	v_mov_b32_e32 v43, v39
	v_pk_add_f32 v[46:47], v[36:37], v[42:43] neg_lo:[0,1] neg_hi:[0,1]
	v_pk_add_f32 v[36:37], v[36:37], v[42:43]
	v_mov_b32_e32 v45, v34
	v_pk_add_f32 v[42:43], v[36:37], v[34:35] op_sel:[1,0] op_sel_hi:[0,1] neg_lo:[0,1] neg_hi:[0,1]
	v_mov_b32_e32 v44, v41
	v_mov_b32_e32 v40, v39
	v_mov_b32_e32 v41, v37
	v_pk_mov_b32 v[34:35], v[34:35], v[42:43] op_sel:[1,0]
	v_pk_add_f32 v[38:39], v[38:39], v[42:43] op_sel_hi:[1,0] neg_lo:[0,1] neg_hi:[0,1]
	v_pk_add_f32 v[34:35], v[40:41], v[34:35] neg_lo:[0,1] neg_hi:[0,1]
	v_mov_b32_e32 v38, v46
	v_pk_add_f32 v[34:35], v[44:45], v[34:35] neg_lo:[0,1] neg_hi:[0,1]
	v_mov_b32_e32 v47, v37
	v_pk_add_f32 v[38:39], v[38:39], v[34:35]
	s_waitcnt vmcnt(3)
	v_lshlrev_b32_e32 v5, 16, v52
	v_pk_add_f32 v[40:41], v[38:39], v[38:39] op_sel:[0,1] op_sel_hi:[1,0]
	v_mul_f32_e32 v43, 0x3db504f3, v5
	v_pk_add_f32 v[36:37], v[36:37], v[40:41] op_sel:[1,0] op_sel_hi:[0,1]
	v_mov_b32_e32 v39, v36
	v_mov_b32_e32 v35, v40
	v_pk_add_f32 v[40:41], v[38:39], v[46:47] neg_lo:[0,1] neg_hi:[0,1]
	s_waitcnt vmcnt(2)
	v_lshlrev_b32_e32 v42, 16, v53
	v_mad_i64_i32 v[254:255], s[34:35], s30, v24, v[16:17]
	global_load_ushort v52, v[254:255], off
	global_load_ushort v53, v[254:255], off offset:1024
	v_sub_f32_e32 v5, v38, v40
	v_pk_add_f32 v[34:35], v[34:35], v[40:41] neg_lo:[0,1] neg_hi:[0,1]
	v_sub_f32_e32 v5, v46, v5
	v_add_f32_e32 v5, v34, v5
	v_add_f32_e32 v5, v5, v35
	v_add_f32_e32 v5, v36, v5
	v_cndmask_b32_e32 v5, v21, v5, vcc
	v_cmp_ngt_f32_e32 vcc, -1.0, v49
	s_nop 1
	v_cndmask_b32_e32 v5, v22, v5, vcc
	v_cmp_neq_f32_e32 vcc, -1.0, v49
	s_nop 1
	v_cndmask_b32_e32 v5, v23, v5, vcc
	v_cmp_lt_f32_e64 vcc, |v49|, s28
	s_nop 1
	v_cndmask_b32_e32 v5, v5, v49, vcc
	v_sub_f32_e32 v5, v48, v5
	v_fmac_f32_e32 v32, 0x3d800000, v5
	v_mul_f32_e32 v5, 0x3fb8aa3b, v32
	v_exp_f32_e32 v5, v5
	s_nop 0
	v_div_scale_f32 v35, s[34:35], v5, v5, v42
	v_rcp_f32_e32 v37, v35
	v_mul_f32_e32 v34, v43, v5
	v_cvt_pk_bf16_f32 v34, v34, s0
	global_store_short v[50:51], v34, off
	v_fma_f32 v34, -v35, v37, 1.0
	v_div_scale_f32 v36, vcc, v42, v5, v42
	v_fmac_f32_e32 v37, v34, v37
	v_mul_f32_e32 v34, v36, v37
	v_fma_f32 v38, -v35, v34, v36
	v_fmac_f32_e32 v34, v38, v37
	v_fma_f32 v35, -v35, v34, v36
	v_div_fmas_f32 v34, v35, v37, v34
	v_div_fixup_f32 v34, v34, v5, v42
	s_and_b64 vcc, exec, s[12:13]
	v_cvt_pk_bf16_f32 v34, v34, s0
	global_store_short v[50:51], v34, off offset:1024
	s_cbranch_vccnz .LBB0_562
	v_lshl_add_u64 v[6:7], v[0:1], 2, s[16:17]
	s_movk_i32 s29, 0x100
	s_mov_b64 s[12:13], 0
	s_and_b64 vcc, exec, s[18:19]
	global_store_dword v[6:7], v5, off
	s_cbranch_vccz .LBB0_561
	s_add_i32 s14, s14, s70
	s_cmpk_gt_i32 s14, 0x407
	s_cbranch_scc0 .LBB0_556

; template <int PH>
; __global__ void __launch_bounds__(256, 2) phase_kernel(Params p) {
;   __shared__ __attribute__((aligned(16))) char smem[SMEM_BYTES];
;   run_phase<PH>(p, smem);
; }
; __global__ void __launch_bounds__(256, 2) hybrid_fwd(Params p) {
;   __shared__ __attribute__((aligned(16))) char smem[SMEM_BYTES];
	.amdhsa_kernel _Z10hybrid_fwd6Params
		.amdhsa_group_segment_fixed_size 66560
		.amdhsa_private_segment_fixed_size 0
		.amdhsa_kernarg_size 456
		.amdhsa_user_sgpr_count 2
		.amdhsa_user_sgpr_dispatch_ptr 0
		.amdhsa_user_sgpr_queue_ptr 0
		.amdhsa_user_sgpr_kernarg_segment_ptr 1
		.amdhsa_user_sgpr_dispatch_id 0
		.amdhsa_user_sgpr_kernarg_preload_length 0
		.amdhsa_user_sgpr_kernarg_preload_offset 0
		.amdhsa_user_sgpr_private_segment_size 0
		.amdhsa_uses_dynamic_stack 0
		.amdhsa_enable_private_segment 0
		.amdhsa_system_sgpr_workgroup_id_x 1
		.amdhsa_system_sgpr_workgroup_id_y 0
		.amdhsa_system_sgpr_workgroup_id_z 0
		.amdhsa_system_sgpr_workgroup_info 0
		.amdhsa_system_vgpr_workitem_id 2
		.amdhsa_next_free_vgpr 256
		.amdhsa_next_free_sgpr 96
		.amdhsa_accum_offset 256
		.amdhsa_reserve_vcc 1
		.amdhsa_float_round_mode_32 0
		.amdhsa_float_round_mode_16_64 0
		.amdhsa_float_denorm_mode_32 3
		.amdhsa_float_denorm_mode_16_64 3
		.amdhsa_dx10_clamp 1
		.amdhsa_ieee_mode 1
		.amdhsa_fp16_overflow 0
		.amdhsa_tg_split 0
		.amdhsa_exception_fp_ieee_invalid_op 0
		.amdhsa_exception_fp_denorm_src 0
		.amdhsa_exception_fp_ieee_div_zero 0
		.amdhsa_exception_fp_ieee_overflow 0
		.amdhsa_exception_fp_ieee_underflow 0
		.amdhsa_exception_fp_ieee_inexact 0
		.amdhsa_exception_int_div_zero 0
	.end_amdhsa_kernel

; template <int PH>
; __global__ void __launch_bounds__(256, 2) phase_kernel(Params p) {
;   __shared__ __attribute__((aligned(16))) char smem[SMEM_BYTES];
;   run_phase<PH>(p, smem);
; }
; __global__ void __launch_bounds__(256, 2) hybrid_fwd(Params p) {
;   __shared__ __attribute__((aligned(16))) char smem[SMEM_BYTES];
amdhsa.kernels:
  - .agpr_count:     0
    .args:
      - .offset:         0
        .size:           200
        .value_kind:     by_value
      - .offset:         200
        .size:           4
        .value_kind:     hidden_block_count_x
      - .offset:         204
        .size:           4
        .value_kind:     hidden_block_count_y
      - .offset:         208
        .size:           4
        .value_kind:     hidden_block_count_z
      - .offset:         212
        .size:           2
        .value_kind:     hidden_group_size_x
      - .offset:         214
        .size:           2
        .value_kind:     hidden_group_size_y
      - .offset:         216
        .size:           2
        .value_kind:     hidden_group_size_z
      - .offset:         218
        .size:           2
        .value_kind:     hidden_remainder_x
      - .offset:         220
        .size:           2
        .value_kind:     hidden_remainder_y
      - .offset:         222
        .size:           2
        .value_kind:     hidden_remainder_z
      - .offset:         240
        .size:           8
        .value_kind:     hidden_global_offset_x
      - .offset:         248
        .size:           8
        .value_kind:     hidden_global_offset_y
      - .offset:         256
        .size:           8
        .value_kind:     hidden_global_offset_z
      - .offset:         264
        .size:           2
        .value_kind:     hidden_grid_dims
      - .offset:         288
        .size:           8
        .value_kind:     hidden_multigrid_sync_arg
    .group_segment_fixed_size: 66560
    .kernarg_segment_align: 8
    .kernarg_segment_size: 456
    .language:       OpenCL C
    .language_version:
      - 2
      - 0
    .max_flat_workgroup_size: 256
    .name:           _Z10hybrid_fwd6Params
    .private_segment_fixed_size: 0
    .sgpr_count:     96
    .sgpr_spill_count: 0
    .symbol:         _Z10hybrid_fwd6Params.kd
    .uniform_work_group_size: 1
    .uses_dynamic_stack: false
    .vgpr_count:     256
    .vgpr_spill_count: 0
    .wavefront_size: 64
